# nt hint on the P4 final-output stores (output is never re-read)
# speedup vs baseline: 1.0067x; 1.0030x over previous
.Lp4_loop:
	ds_bpermute_b32 v46, v199, v48
	s_waitcnt lgkmcnt(0)
	v_add_f32_e32 v27, v48, v46
	ds_bpermute_b32 v46, v200, v27
	s_waitcnt lgkmcnt(0)
	v_add_f32_e32 v27, v27, v46
	ds_bpermute_b32 v46, v201, v27
	s_waitcnt lgkmcnt(0)
	v_add_f32_e32 v27, v27, v46
	ds_bpermute_b32 v46, v202, v27
	s_waitcnt lgkmcnt(0)
	v_add_f32_e32 v27, v27, v46
	v_fmamk_f32 v27, v27, 0x3a800000, v22
	v_mul_f32_e32 v46, 0x4b800000, v27
	v_cmp_gt_f32_e32 vcc, s3, v27
	s_nop 1
	v_cndmask_b32_e32 v27, v27, v46, vcc
	v_rsq_f32_e32 v27, v27
	s_nop 0
	v_mul_f32_e32 v46, 0x45800000, v27
	v_cndmask_b32_e32 v46, v27, v46, vcc
	v_lshlrev_b32_e32 v44, 16, v52
	v_and_b32_e32 v45, 0xffff0000, v52
	v_lshlrev_b32_e32 v40, 16, v53
	v_and_b32_e32 v41, 0xffff0000, v53
	v_pk_mul_f32 v[40:41], v[46:47], v[40:41] op_sel_hi:[0,1]
	v_pk_mul_f32 v[44:45], v[46:47], v[44:45] op_sel_hi:[0,1]
	v_pk_mul_f32 v[44:45], v[0:1], v[44:45]
	v_pk_mul_f32 v[40:41], v[2:3], v[40:41]
	v_pk_fma_f32 v[60:61], v[76:77], v[44:45], v[60:61]
	v_pk_fma_f32 v[62:63], v[78:79], v[40:41], v[62:63]
	global_store_dwordx4 v[50:51], v[60:63], off nt
	v_lshlrev_b32_e32 v44, 16, v54
	v_and_b32_e32 v45, 0xffff0000, v54
	v_lshlrev_b32_e32 v40, 16, v55
	v_and_b32_e32 v41, 0xffff0000, v55
	v_pk_mul_f32 v[40:41], v[46:47], v[40:41] op_sel_hi:[0,1]
	v_pk_mul_f32 v[44:45], v[46:47], v[44:45] op_sel_hi:[0,1]
	v_pk_mul_f32 v[44:45], v[4:5], v[44:45]
	v_pk_mul_f32 v[40:41], v[6:7], v[40:41]
	v_pk_fma_f32 v[64:65], v[80:81], v[44:45], v[64:65]
	v_pk_fma_f32 v[66:67], v[82:83], v[40:41], v[66:67]
	global_store_dwordx4 v[50:51], v[64:67], off offset:1024 nt
	v_lshlrev_b32_e32 v44, 16, v56
	v_and_b32_e32 v45, 0xffff0000, v56
	v_lshlrev_b32_e32 v40, 16, v57
	v_and_b32_e32 v41, 0xffff0000, v57
	v_pk_mul_f32 v[40:41], v[46:47], v[40:41] op_sel_hi:[0,1]
	v_pk_mul_f32 v[44:45], v[46:47], v[44:45] op_sel_hi:[0,1]
	v_pk_mul_f32 v[44:45], v[8:9], v[44:45]
	v_pk_mul_f32 v[40:41], v[10:11], v[40:41]
	v_pk_fma_f32 v[68:69], v[84:85], v[44:45], v[68:69]
	v_pk_fma_f32 v[70:71], v[86:87], v[40:41], v[70:71]
	global_store_dwordx4 v[50:51], v[68:71], off offset:2048 nt
	v_lshlrev_b32_e32 v44, 16, v58
	v_and_b32_e32 v45, 0xffff0000, v58
	v_lshlrev_b32_e32 v40, 16, v59
	v_and_b32_e32 v41, 0xffff0000, v59
	v_pk_mul_f32 v[40:41], v[46:47], v[40:41] op_sel_hi:[0,1]
	v_pk_mul_f32 v[44:45], v[46:47], v[44:45] op_sel_hi:[0,1]
	v_pk_mul_f32 v[44:45], v[12:13], v[44:45]
	v_pk_mul_f32 v[40:41], v[14:15], v[40:41]
	v_pk_fma_f32 v[72:73], v[88:89], v[44:45], v[72:73]
	v_pk_fma_f32 v[74:75], v[90:91], v[40:41], v[74:75]
	global_store_dwordx4 v[50:51], v[72:75], off offset:3072 nt
	s_cmp_lt_i32 s2, 0x8000
	s_cbranch_scc0 .Lp4_final_b
	v_lshl_add_u64 v[28:29], s[44:45], 0, v[18:19]
	global_load_dword v48, v[28:29], off
	s_ashr_i32 s12, s2, 11
	s_mulk_i32 s12, 0xc00
	s_ashr_i32 s13, s12, 31
	s_lshl_b64 s[12:13], s[12:13], 2
	s_add_u32 s12, s44, s12
	s_addc_u32 s13, s45, s13
	s_add_u32 s12, s12, 0x2000
	s_addc_u32 s13, s13, 0
	v_lshl_add_u64 v[32:33], s[44:45], 0, v[20:21]
	v_add_co_u32_e32 v38, vcc, s14, v32
	s_nop 1
	v_addc_co_u32_e32 v39, vcc, 0, v33, vcc
	global_load_dwordx2 v[52:53], v[38:39], off
	global_load_dwordx2 v[54:55], v[38:39], off offset:512
	global_load_dwordx2 v[56:57], v[38:39], off offset:1024
	global_load_dwordx2 v[58:59], v[38:39], off offset:1536
	v_lshl_add_u64 v[36:37], s[10:11], 0, v[16:17]
	global_load_dwordx4 v[60:63], v[36:37], off
	global_load_dwordx4 v[64:67], v[36:37], off offset:1024
	global_load_dwordx4 v[68:71], v[36:37], off offset:2048
	global_load_dwordx4 v[72:75], v[36:37], off offset:3072
	global_load_dwordx4 v[76:79], v23, s[12:13]
	global_load_dwordx4 v[80:83], v24, s[12:13]
	global_load_dwordx4 v[84:87], v25, s[12:13]
	global_load_dwordx4 v[88:91], v26, s[12:13]
	v_lshl_add_u64 v[50:51], s[4:5], 0, v[16:17]
	s_add_i32 s2, s2, s48
	s_add_u32 s4, s4, s6
	s_addc_u32 s5, s5, s7
	s_add_u32 s10, s10, s6
	s_addc_u32 s11, s11, s7
	v_lshl_add_u64 v[18:19], v[18:19], 0, s[0:1]
	v_lshl_add_u64 v[20:21], v[20:21], 0, s[8:9]
	s_waitcnt vmcnt(17)
	ds_bpermute_b32 v46, v199, v96
	s_waitcnt lgkmcnt(0)
	v_add_f32_e32 v27, v96, v46
	ds_bpermute_b32 v46, v200, v27
	s_waitcnt lgkmcnt(0)
	v_add_f32_e32 v27, v27, v46
	ds_bpermute_b32 v46, v201, v27
	s_waitcnt lgkmcnt(0)
	v_add_f32_e32 v27, v27, v46
	ds_bpermute_b32 v46, v202, v27
	s_waitcnt lgkmcnt(0)
	v_add_f32_e32 v27, v27, v46
	v_fmamk_f32 v27, v27, 0x3a800000, v22
	v_mul_f32_e32 v46, 0x4b800000, v27
	v_cmp_gt_f32_e32 vcc, s3, v27
	s_nop 1
	v_cndmask_b32_e32 v27, v27, v46, vcc
	v_rsq_f32_e32 v27, v27
	s_nop 0
	v_mul_f32_e32 v46, 0x45800000, v27
	v_cndmask_b32_e32 v46, v27, v46, vcc
	v_lshlrev_b32_e32 v44, 16, v100
	v_and_b32_e32 v45, 0xffff0000, v100
	v_lshlrev_b32_e32 v40, 16, v101
	v_and_b32_e32 v41, 0xffff0000, v101
	v_pk_mul_f32 v[40:41], v[46:47], v[40:41] op_sel_hi:[0,1]
	v_pk_mul_f32 v[44:45], v[46:47], v[44:45] op_sel_hi:[0,1]
	v_pk_mul_f32 v[44:45], v[0:1], v[44:45]
	v_pk_mul_f32 v[40:41], v[2:3], v[40:41]
	v_pk_fma_f32 v[108:109], v[124:125], v[44:45], v[108:109]
	v_pk_fma_f32 v[110:111], v[126:127], v[40:41], v[110:111]
	global_store_dwordx4 v[98:99], v[108:111], off nt
	v_lshlrev_b32_e32 v44, 16, v102
	v_and_b32_e32 v45, 0xffff0000, v102
	v_lshlrev_b32_e32 v40, 16, v103
	v_and_b32_e32 v41, 0xffff0000, v103
	v_pk_mul_f32 v[40:41], v[46:47], v[40:41] op_sel_hi:[0,1]
	v_pk_mul_f32 v[44:45], v[46:47], v[44:45] op_sel_hi:[0,1]
	v_pk_mul_f32 v[44:45], v[4:5], v[44:45]
	v_pk_mul_f32 v[40:41], v[6:7], v[40:41]
	v_pk_fma_f32 v[112:113], v[128:129], v[44:45], v[112:113]
	v_pk_fma_f32 v[114:115], v[130:131], v[40:41], v[114:115]
	global_store_dwordx4 v[98:99], v[112:115], off offset:1024 nt
	v_lshlrev_b32_e32 v44, 16, v104
	v_and_b32_e32 v45, 0xffff0000, v104
	v_lshlrev_b32_e32 v40, 16, v105
	v_and_b32_e32 v41, 0xffff0000, v105
	v_pk_mul_f32 v[40:41], v[46:47], v[40:41] op_sel_hi:[0,1]
	v_pk_mul_f32 v[44:45], v[46:47], v[44:45] op_sel_hi:[0,1]
	v_pk_mul_f32 v[44:45], v[8:9], v[44:45]
	v_pk_mul_f32 v[40:41], v[10:11], v[40:41]
	v_pk_fma_f32 v[116:117], v[132:133], v[44:45], v[116:117]
	v_pk_fma_f32 v[118:119], v[134:135], v[40:41], v[118:119]
	global_store_dwordx4 v[98:99], v[116:119], off offset:2048 nt
	v_lshlrev_b32_e32 v44, 16, v106
	v_and_b32_e32 v45, 0xffff0000, v106
	v_lshlrev_b32_e32 v40, 16, v107
	v_and_b32_e32 v41, 0xffff0000, v107
	v_pk_mul_f32 v[40:41], v[46:47], v[40:41] op_sel_hi:[0,1]
	v_pk_mul_f32 v[44:45], v[46:47], v[44:45] op_sel_hi:[0,1]
	v_pk_mul_f32 v[44:45], v[12:13], v[44:45]
	v_pk_mul_f32 v[40:41], v[14:15], v[40:41]
	v_pk_fma_f32 v[120:121], v[136:137], v[44:45], v[120:121]
	v_pk_fma_f32 v[122:123], v[138:139], v[40:41], v[122:123]
	global_store_dwordx4 v[98:99], v[120:123], off offset:3072 nt
	s_cmp_lt_i32 s2, 0x8000
	s_cbranch_scc0 .Lp4_final_a
	v_lshl_add_u64 v[28:29], s[44:45], 0, v[18:19]
	global_load_dword v96, v[28:29], off
	s_ashr_i32 s12, s2, 11
	s_mulk_i32 s12, 0xc00
	s_ashr_i32 s13, s12, 31
	s_lshl_b64 s[12:13], s[12:13], 2
	s_add_u32 s12, s44, s12
	s_addc_u32 s13, s45, s13
	s_add_u32 s12, s12, 0x2000
	s_addc_u32 s13, s13, 0
	v_lshl_add_u64 v[32:33], s[44:45], 0, v[20:21]
	v_add_co_u32_e32 v38, vcc, s14, v32
	s_nop 1
	v_addc_co_u32_e32 v39, vcc, 0, v33, vcc
	global_load_dwordx2 v[100:101], v[38:39], off
	global_load_dwordx2 v[102:103], v[38:39], off offset:512
	global_load_dwordx2 v[104:105], v[38:39], off offset:1024
	global_load_dwordx2 v[106:107], v[38:39], off offset:1536
	v_lshl_add_u64 v[36:37], s[10:11], 0, v[16:17]
	global_load_dwordx4 v[108:111], v[36:37], off
	global_load_dwordx4 v[112:115], v[36:37], off offset:1024
	global_load_dwordx4 v[116:119], v[36:37], off offset:2048
	global_load_dwordx4 v[120:123], v[36:37], off offset:3072
	global_load_dwordx4 v[124:127], v23, s[12:13]
	global_load_dwordx4 v[128:131], v24, s[12:13]
	global_load_dwordx4 v[132:135], v25, s[12:13]
	global_load_dwordx4 v[136:139], v26, s[12:13]
	v_lshl_add_u64 v[98:99], s[4:5], 0, v[16:17]
	s_add_i32 s2, s2, s48
	s_add_u32 s4, s4, s6
	s_addc_u32 s5, s5, s7
	s_add_u32 s10, s10, s6
	s_addc_u32 s11, s11, s7
	v_lshl_add_u64 v[18:19], v[18:19], 0, s[0:1]
	v_lshl_add_u64 v[20:21], v[20:21], 0, s[8:9]
	s_waitcnt vmcnt(17)
	s_branch .Lp4_loop
.Lp4_final_a:
	s_waitcnt vmcnt(0)
	ds_bpermute_b32 v46, v199, v48
	s_waitcnt lgkmcnt(0)
	v_add_f32_e32 v27, v48, v46
	ds_bpermute_b32 v46, v200, v27
	s_waitcnt lgkmcnt(0)
	v_add_f32_e32 v27, v27, v46
	ds_bpermute_b32 v46, v201, v27
	s_waitcnt lgkmcnt(0)
	v_add_f32_e32 v27, v27, v46
	ds_bpermute_b32 v46, v202, v27
	s_waitcnt lgkmcnt(0)
	v_add_f32_e32 v27, v27, v46
	v_fmamk_f32 v27, v27, 0x3a800000, v22
	v_mul_f32_e32 v46, 0x4b800000, v27
	v_cmp_gt_f32_e32 vcc, s3, v27
	s_nop 1
	v_cndmask_b32_e32 v27, v27, v46, vcc
	v_rsq_f32_e32 v27, v27
	s_nop 0
	v_mul_f32_e32 v46, 0x45800000, v27
	v_cndmask_b32_e32 v46, v27, v46, vcc
	v_lshlrev_b32_e32 v44, 16, v52
	v_and_b32_e32 v45, 0xffff0000, v52
	v_lshlrev_b32_e32 v40, 16, v53
	v_and_b32_e32 v41, 0xffff0000, v53
	v_pk_mul_f32 v[40:41], v[46:47], v[40:41] op_sel_hi:[0,1]
	v_pk_mul_f32 v[44:45], v[46:47], v[44:45] op_sel_hi:[0,1]
	v_pk_mul_f32 v[44:45], v[0:1], v[44:45]
	v_pk_mul_f32 v[40:41], v[2:3], v[40:41]
	v_pk_fma_f32 v[60:61], v[76:77], v[44:45], v[60:61]
	v_pk_fma_f32 v[62:63], v[78:79], v[40:41], v[62:63]
	global_store_dwordx4 v[50:51], v[60:63], off nt
	v_lshlrev_b32_e32 v44, 16, v54
	v_and_b32_e32 v45, 0xffff0000, v54
	v_lshlrev_b32_e32 v40, 16, v55
	v_and_b32_e32 v41, 0xffff0000, v55
	v_pk_mul_f32 v[40:41], v[46:47], v[40:41] op_sel_hi:[0,1]
	v_pk_mul_f32 v[44:45], v[46:47], v[44:45] op_sel_hi:[0,1]
	v_pk_mul_f32 v[44:45], v[4:5], v[44:45]
	v_pk_mul_f32 v[40:41], v[6:7], v[40:41]
	v_pk_fma_f32 v[64:65], v[80:81], v[44:45], v[64:65]
	v_pk_fma_f32 v[66:67], v[82:83], v[40:41], v[66:67]
	global_store_dwordx4 v[50:51], v[64:67], off offset:1024 nt
	v_lshlrev_b32_e32 v44, 16, v56
	v_and_b32_e32 v45, 0xffff0000, v56
	v_lshlrev_b32_e32 v40, 16, v57
	v_and_b32_e32 v41, 0xffff0000, v57
	v_pk_mul_f32 v[40:41], v[46:47], v[40:41] op_sel_hi:[0,1]
	v_pk_mul_f32 v[44:45], v[46:47], v[44:45] op_sel_hi:[0,1]
	v_pk_mul_f32 v[44:45], v[8:9], v[44:45]
	v_pk_mul_f32 v[40:41], v[10:11], v[40:41]
	v_pk_fma_f32 v[68:69], v[84:85], v[44:45], v[68:69]
	v_pk_fma_f32 v[70:71], v[86:87], v[40:41], v[70:71]
	global_store_dwordx4 v[50:51], v[68:71], off offset:2048 nt
	v_lshlrev_b32_e32 v44, 16, v58
	v_and_b32_e32 v45, 0xffff0000, v58
	v_lshlrev_b32_e32 v40, 16, v59
	v_and_b32_e32 v41, 0xffff0000, v59
	v_pk_mul_f32 v[40:41], v[46:47], v[40:41] op_sel_hi:[0,1]
	v_pk_mul_f32 v[44:45], v[46:47], v[44:45] op_sel_hi:[0,1]
	v_pk_mul_f32 v[44:45], v[12:13], v[44:45]
	v_pk_mul_f32 v[40:41], v[14:15], v[40:41]
	v_pk_fma_f32 v[72:73], v[88:89], v[44:45], v[72:73]
	v_pk_fma_f32 v[74:75], v[90:91], v[40:41], v[74:75]
	global_store_dwordx4 v[50:51], v[72:75], off offset:3072 nt
	s_endpgm
.Lp4_final_b:
	s_waitcnt vmcnt(0)
	ds_bpermute_b32 v46, v199, v96
	s_waitcnt lgkmcnt(0)
	v_add_f32_e32 v27, v96, v46
	ds_bpermute_b32 v46, v200, v27
	s_waitcnt lgkmcnt(0)
	v_add_f32_e32 v27, v27, v46
	ds_bpermute_b32 v46, v201, v27
	s_waitcnt lgkmcnt(0)
	v_add_f32_e32 v27, v27, v46
	ds_bpermute_b32 v46, v202, v27
	s_waitcnt lgkmcnt(0)
	v_add_f32_e32 v27, v27, v46
	v_fmamk_f32 v27, v27, 0x3a800000, v22
	v_mul_f32_e32 v46, 0x4b800000, v27
	v_cmp_gt_f32_e32 vcc, s3, v27
	s_nop 1
	v_cndmask_b32_e32 v27, v27, v46, vcc
	v_rsq_f32_e32 v27, v27
	s_nop 0
	v_mul_f32_e32 v46, 0x45800000, v27
	v_cndmask_b32_e32 v46, v27, v46, vcc
	v_lshlrev_b32_e32 v44, 16, v100
	v_and_b32_e32 v45, 0xffff0000, v100
	v_lshlrev_b32_e32 v40, 16, v101
	v_and_b32_e32 v41, 0xffff0000, v101
	v_pk_mul_f32 v[40:41], v[46:47], v[40:41] op_sel_hi:[0,1]
	v_pk_mul_f32 v[44:45], v[46:47], v[44:45] op_sel_hi:[0,1]
	v_pk_mul_f32 v[44:45], v[0:1], v[44:45]
	v_pk_mul_f32 v[40:41], v[2:3], v[40:41]
	v_pk_fma_f32 v[108:109], v[124:125], v[44:45], v[108:109]
	v_pk_fma_f32 v[110:111], v[126:127], v[40:41], v[110:111]
	global_store_dwordx4 v[98:99], v[108:111], off nt
	v_lshlrev_b32_e32 v44, 16, v102
	v_and_b32_e32 v45, 0xffff0000, v102
	v_lshlrev_b32_e32 v40, 16, v103
	v_and_b32_e32 v41, 0xffff0000, v103
	v_pk_mul_f32 v[40:41], v[46:47], v[40:41] op_sel_hi:[0,1]
	v_pk_mul_f32 v[44:45], v[46:47], v[44:45] op_sel_hi:[0,1]
	v_pk_mul_f32 v[44:45], v[4:5], v[44:45]
	v_pk_mul_f32 v[40:41], v[6:7], v[40:41]
	v_pk_fma_f32 v[112:113], v[128:129], v[44:45], v[112:113]
	v_pk_fma_f32 v[114:115], v[130:131], v[40:41], v[114:115]
	global_store_dwordx4 v[98:99], v[112:115], off offset:1024 nt
	v_lshlrev_b32_e32 v44, 16, v104
	v_and_b32_e32 v45, 0xffff0000, v104
	v_lshlrev_b32_e32 v40, 16, v105
	v_and_b32_e32 v41, 0xffff0000, v105
	v_pk_mul_f32 v[40:41], v[46:47], v[40:41] op_sel_hi:[0,1]
	v_pk_mul_f32 v[44:45], v[46:47], v[44:45] op_sel_hi:[0,1]
	v_pk_mul_f32 v[44:45], v[8:9], v[44:45]
	v_pk_mul_f32 v[40:41], v[10:11], v[40:41]
	v_pk_fma_f32 v[116:117], v[132:133], v[44:45], v[116:117]
	v_pk_fma_f32 v[118:119], v[134:135], v[40:41], v[118:119]
	global_store_dwordx4 v[98:99], v[116:119], off offset:2048 nt
	v_lshlrev_b32_e32 v44, 16, v106
	v_and_b32_e32 v45, 0xffff0000, v106
	v_lshlrev_b32_e32 v40, 16, v107
	v_and_b32_e32 v41, 0xffff0000, v107
	v_pk_mul_f32 v[40:41], v[46:47], v[40:41] op_sel_hi:[0,1]
	v_pk_mul_f32 v[44:45], v[46:47], v[44:45] op_sel_hi:[0,1]
	v_pk_mul_f32 v[44:45], v[12:13], v[44:45]
	v_pk_mul_f32 v[40:41], v[14:15], v[40:41]
	v_pk_fma_f32 v[120:121], v[136:137], v[44:45], v[120:121]
	v_pk_fma_f32 v[122:123], v[138:139], v[40:41], v[122:123]
	global_store_dwordx4 v[98:99], v[120:123], off offset:3072 nt
	s_endpgm
